# K-loop header aligned to a 64-byte boundary
# baseline (speedup 1.0000x reference)
.Llora_n:
	s_add_u32 s10, s78, 0x80
	s_addc_u32 s11, s79, 0
	s_add_u32 s84, s84, 0x100
	s_addc_u32 s85, s85, 0
	s_mov_b32 s78, 0
	s_add_i32 s72, s78, 2
	s_add_u32 s79, s10, 0x80
	s_addc_u32 vcc_lo, s11, 0
	v_add_u32_e32 v148, 0x10000, v185
	s_cmp_eq_u32 s15, s78
	s_cselect_b32 s78, s12, s84
	s_cselect_b32 vcc_hi, s49, vcc_lo
	s_cselect_b32 vcc_lo, s48, s79
	s_cselect_b32 s79, s13, s85
	s_setprio 2
	ds_read_b128 v[128:131], v148 offset:0
	ds_read_b128 v[132:135], v148 offset:1024
	ds_read_b128 v[136:139], v148 offset:2048
	ds_read_b128 v[140:143], v148 offset:3072
	ds_read_b128 v[218:221], v148 offset:16384
	ds_read_b128 v[222:225], v148 offset:17408
	ds_read_b128 v[226:229], v148 offset:18432
	ds_read_b128 v[230:233], v148 offset:19456
	ds_read_b128 v[162:165], v188 offset:0
	ds_read_b128 v[190:193], v188 offset:1024
	ds_read_b128 v[194:197], v188 offset:2048
	ds_read_b128 v[198:201], v188 offset:3072
	ds_read_b128 v[202:205], v188 offset:4096
	ds_read_b128 v[206:209], v188 offset:5120
	ds_read_b128 v[210:213], v188 offset:6144
	ds_read_b128 v[214:217], v188 offset:7168
	s_add_u32 s4, s10, s26
	s_addc_u32 s5, s11, 0
	s_add_i32 m0, s81, 0xc000
	s_nop 0
	global_load_lds_dwordx4 v152, s[4:5]
	s_add_i32 m0, s81, 0xe000
	s_nop 0
	global_load_lds_dwordx4 v144, s[4:5]
	s_setprio 0
	s_waitcnt vmcnt(8)
	s_waitcnt lgkmcnt(0)
	s_barrier
	v_mfma_f32_16x16x32_bf16 v[124:127], v[128:131], v[162:165], 0
	v_mfma_f32_16x16x32_bf16 v[116:119], v[136:139], v[162:165], 0
	v_mfma_f32_16x16x32_bf16 v[120:123], v[128:131], v[194:197], 0
	v_mfma_f32_16x16x32_bf16 v[112:115], v[136:139], v[194:197], 0
	v_mfma_f32_16x16x32_bf16 v[92:95], v[128:131], v[202:205], 0
	v_mfma_f32_16x16x32_bf16 v[84:87], v[136:139], v[202:205], 0
	v_mfma_f32_16x16x32_bf16 v[88:91], v[128:131], v[210:213], 0
	v_mfma_f32_16x16x32_bf16 v[80:83], v[136:139], v[210:213], 0
	v_mfma_f32_16x16x32_bf16 v[124:127], v[132:135], v[190:193], v[124:127]
	v_mfma_f32_16x16x32_bf16 v[116:119], v[140:143], v[190:193], v[116:119]
	v_mfma_f32_16x16x32_bf16 v[120:123], v[132:135], v[198:201], v[120:123]
	v_mfma_f32_16x16x32_bf16 v[112:115], v[140:143], v[198:201], v[112:115]
	v_mfma_f32_16x16x32_bf16 v[92:95], v[132:135], v[206:209], v[92:95]
	v_mfma_f32_16x16x32_bf16 v[84:87], v[140:143], v[206:209], v[84:87]
	v_mfma_f32_16x16x32_bf16 v[88:91], v[132:135], v[214:217], v[88:91]
	v_mfma_f32_16x16x32_bf16 v[80:83], v[140:143], v[214:217], v[80:83]
	v_mfma_f32_16x16x32_bf16 v[108:111], v[218:221], v[162:165], 0
	v_mfma_f32_16x16x32_bf16 v[100:103], v[226:229], v[162:165], 0
	v_mfma_f32_16x16x32_bf16 v[104:107], v[218:221], v[194:197], 0
	v_mfma_f32_16x16x32_bf16 v[96:99], v[226:229], v[194:197], 0
	v_mfma_f32_16x16x32_bf16 v[76:79], v[218:221], v[202:205], 0
	v_mfma_f32_16x16x32_bf16 v[68:71], v[226:229], v[202:205], 0
	v_mfma_f32_16x16x32_bf16 v[72:75], v[218:221], v[210:213], 0
	v_mfma_f32_16x16x32_bf16 v[64:67], v[226:229], v[210:213], 0
	v_mfma_f32_16x16x32_bf16 v[108:111], v[222:225], v[190:193], v[108:111]
	v_mfma_f32_16x16x32_bf16 v[100:103], v[230:233], v[190:193], v[100:103]
	v_mfma_f32_16x16x32_bf16 v[104:107], v[222:225], v[198:201], v[104:107]
	v_mfma_f32_16x16x32_bf16 v[96:99], v[230:233], v[198:201], v[96:99]
	v_mfma_f32_16x16x32_bf16 v[76:79], v[222:225], v[206:209], v[76:79]
	v_mfma_f32_16x16x32_bf16 v[68:71], v[230:233], v[206:209], v[68:71]
	v_mfma_f32_16x16x32_bf16 v[72:75], v[222:225], v[214:217], v[72:75]
	v_mfma_f32_16x16x32_bf16 v[64:67], v[230:233], v[214:217], v[64:67]
	s_barrier
	s_setprio 2
	ds_read_b128 v[162:165], v188 offset:16384
	ds_read_b128 v[190:193], v188 offset:17408
	ds_read_b128 v[194:197], v188 offset:18432
	ds_read_b128 v[198:201], v188 offset:19456
	ds_read_b128 v[202:205], v188 offset:20480
	ds_read_b128 v[206:209], v188 offset:21504
	ds_read_b128 v[210:213], v188 offset:22528
	ds_read_b128 v[214:217], v188 offset:23552
	s_add_i32 m0, s81, 0x10000
	s_nop 0
	global_load_lds_dwordx4 v154, s[78:79]
	s_add_i32 m0, s81, 0x12000
	s_nop 0
	global_load_lds_dwordx4 v146, s[78:79]
	s_add_i32 m0, s81, 0x0
	s_nop 0
	global_load_lds_dwordx4 v152, vcc
	s_add_i32 m0, s81, 0x2000
	s_nop 0
	global_load_lds_dwordx4 v144, vcc
	s_add_u32 s4, s78, s26
	s_addc_u32 s5, s79, 0
	s_add_i32 m0, s81, 0x14000
	s_nop 0
	global_load_lds_dwordx4 v154, s[4:5]
	s_add_i32 m0, s81, 0x16000
	s_nop 0
	global_load_lds_dwordx4 v146, s[4:5]
	s_setprio 0
	s_waitcnt vmcnt(8)
	s_waitcnt lgkmcnt(0)
	s_barrier
	v_mfma_f32_16x16x32_bf16 v[60:63], v[128:131], v[162:165], 0
	v_mfma_f32_16x16x32_bf16 v[56:59], v[136:139], v[162:165], 0
	v_mfma_f32_16x16x32_bf16 v[52:55], v[128:131], v[194:197], 0
	v_mfma_f32_16x16x32_bf16 v[48:51], v[136:139], v[194:197], 0
	v_mfma_f32_16x16x32_bf16 v[28:31], v[128:131], v[202:205], 0
	v_mfma_f32_16x16x32_bf16 v[20:23], v[136:139], v[202:205], 0
	v_mfma_f32_16x16x32_bf16 v[24:27], v[128:131], v[210:213], 0
	v_mfma_f32_16x16x32_bf16 v[16:19], v[136:139], v[210:213], 0
	v_mfma_f32_16x16x32_bf16 v[60:63], v[132:135], v[190:193], v[60:63]
	v_mfma_f32_16x16x32_bf16 v[56:59], v[140:143], v[190:193], v[56:59]
	v_mfma_f32_16x16x32_bf16 v[52:55], v[132:135], v[198:201], v[52:55]
	v_mfma_f32_16x16x32_bf16 v[48:51], v[140:143], v[198:201], v[48:51]
	v_mfma_f32_16x16x32_bf16 v[28:31], v[132:135], v[206:209], v[28:31]
	v_mfma_f32_16x16x32_bf16 v[20:23], v[140:143], v[206:209], v[20:23]
	v_mfma_f32_16x16x32_bf16 v[24:27], v[132:135], v[214:217], v[24:27]
	v_mfma_f32_16x16x32_bf16 v[16:19], v[140:143], v[214:217], v[16:19]
	v_mfma_f32_16x16x32_bf16 v[44:47], v[218:221], v[162:165], 0
	v_mfma_f32_16x16x32_bf16 v[36:39], v[226:229], v[162:165], 0
	v_mfma_f32_16x16x32_bf16 v[40:43], v[218:221], v[194:197], 0
	v_mfma_f32_16x16x32_bf16 v[32:35], v[226:229], v[194:197], 0
	v_mfma_f32_16x16x32_bf16 v[12:15], v[218:221], v[202:205], 0
	v_mfma_f32_16x16x32_bf16 v[4:7], v[226:229], v[202:205], 0
	v_mfma_f32_16x16x32_bf16 v[8:11], v[218:221], v[210:213], 0
	v_mfma_f32_16x16x32_bf16 v[0:3], v[226:229], v[210:213], 0
	v_mfma_f32_16x16x32_bf16 v[44:47], v[222:225], v[190:193], v[44:47]
	v_mfma_f32_16x16x32_bf16 v[36:39], v[230:233], v[190:193], v[36:39]
	v_mfma_f32_16x16x32_bf16 v[40:43], v[222:225], v[198:201], v[40:43]
	v_mfma_f32_16x16x32_bf16 v[32:35], v[230:233], v[198:201], v[32:35]
	v_mfma_f32_16x16x32_bf16 v[12:15], v[222:225], v[206:209], v[12:15]
	v_mfma_f32_16x16x32_bf16 v[4:7], v[230:233], v[206:209], v[4:7]
	v_mfma_f32_16x16x32_bf16 v[8:11], v[222:225], v[214:217], v[8:11]
	v_mfma_f32_16x16x32_bf16 v[0:3], v[230:233], v[214:217], v[0:3]
	s_barrier
	s_setprio 2
	ds_read_b128 v[128:131], v148 offset:32768
	ds_read_b128 v[132:135], v148 offset:33792
	ds_read_b128 v[136:139], v148 offset:34816
	ds_read_b128 v[140:143], v148 offset:35840
	ds_read_b128 v[218:221], v148 offset:49152
	ds_read_b128 v[222:225], v148 offset:50176
	ds_read_b128 v[226:229], v148 offset:51200
	ds_read_b128 v[230:233], v148 offset:52224
	ds_read_b128 v[162:165], v188 offset:32768
	ds_read_b128 v[190:193], v188 offset:33792
	ds_read_b128 v[194:197], v188 offset:34816
	ds_read_b128 v[198:201], v188 offset:35840
	ds_read_b128 v[202:205], v188 offset:36864
	ds_read_b128 v[206:209], v188 offset:37888
	ds_read_b128 v[210:213], v188 offset:38912
	ds_read_b128 v[214:217], v188 offset:39936
	s_add_u32 s4, vcc_lo, s26
	s_addc_u32 s5, vcc_hi, 0
	s_add_i32 m0, s81, 0x4000
	s_nop 0
	global_load_lds_dwordx4 v152, s[4:5]
	s_add_i32 m0, s81, 0x6000
	s_nop 0
	global_load_lds_dwordx4 v144, s[4:5]
	s_setprio 0
	s_waitcnt vmcnt(8)
	s_waitcnt lgkmcnt(0)
	s_barrier
	v_mfma_f32_16x16x32_bf16 v[124:127], v[128:131], v[162:165], v[124:127]
	v_mfma_f32_16x16x32_bf16 v[116:119], v[136:139], v[162:165], v[116:119]
	v_mfma_f32_16x16x32_bf16 v[120:123], v[128:131], v[194:197], v[120:123]
	v_mfma_f32_16x16x32_bf16 v[112:115], v[136:139], v[194:197], v[112:115]
	v_mfma_f32_16x16x32_bf16 v[92:95], v[128:131], v[202:205], v[92:95]
	v_mfma_f32_16x16x32_bf16 v[84:87], v[136:139], v[202:205], v[84:87]
	v_mfma_f32_16x16x32_bf16 v[88:91], v[128:131], v[210:213], v[88:91]
	v_mfma_f32_16x16x32_bf16 v[80:83], v[136:139], v[210:213], v[80:83]
	v_mfma_f32_16x16x32_bf16 v[124:127], v[132:135], v[190:193], v[124:127]
	v_mfma_f32_16x16x32_bf16 v[116:119], v[140:143], v[190:193], v[116:119]
	v_mfma_f32_16x16x32_bf16 v[120:123], v[132:135], v[198:201], v[120:123]
	v_mfma_f32_16x16x32_bf16 v[112:115], v[140:143], v[198:201], v[112:115]
	v_mfma_f32_16x16x32_bf16 v[92:95], v[132:135], v[206:209], v[92:95]
	v_mfma_f32_16x16x32_bf16 v[84:87], v[140:143], v[206:209], v[84:87]
	v_mfma_f32_16x16x32_bf16 v[88:91], v[132:135], v[214:217], v[88:91]
	v_mfma_f32_16x16x32_bf16 v[80:83], v[140:143], v[214:217], v[80:83]
	v_mfma_f32_16x16x32_bf16 v[108:111], v[218:221], v[162:165], v[108:111]
	v_mfma_f32_16x16x32_bf16 v[100:103], v[226:229], v[162:165], v[100:103]
	v_mfma_f32_16x16x32_bf16 v[104:107], v[218:221], v[194:197], v[104:107]
	v_mfma_f32_16x16x32_bf16 v[96:99], v[226:229], v[194:197], v[96:99]
	v_mfma_f32_16x16x32_bf16 v[76:79], v[218:221], v[202:205], v[76:79]
	v_mfma_f32_16x16x32_bf16 v[68:71], v[226:229], v[202:205], v[68:71]
	v_mfma_f32_16x16x32_bf16 v[72:75], v[218:221], v[210:213], v[72:75]
	v_mfma_f32_16x16x32_bf16 v[64:67], v[226:229], v[210:213], v[64:67]
	v_mfma_f32_16x16x32_bf16 v[108:111], v[222:225], v[190:193], v[108:111]
	v_mfma_f32_16x16x32_bf16 v[100:103], v[230:233], v[190:193], v[100:103]
	v_mfma_f32_16x16x32_bf16 v[104:107], v[222:225], v[198:201], v[104:107]
	v_mfma_f32_16x16x32_bf16 v[96:99], v[230:233], v[198:201], v[96:99]
	v_mfma_f32_16x16x32_bf16 v[76:79], v[222:225], v[206:209], v[76:79]
	v_mfma_f32_16x16x32_bf16 v[68:71], v[230:233], v[206:209], v[68:71]
	v_mfma_f32_16x16x32_bf16 v[72:75], v[222:225], v[214:217], v[72:75]
	v_mfma_f32_16x16x32_bf16 v[64:67], v[230:233], v[214:217], v[64:67]
	s_barrier
	s_setprio 2
	ds_read_b128 v[162:165], v188 offset:49152
	ds_read_b128 v[190:193], v188 offset:50176
	ds_read_b128 v[194:197], v188 offset:51200
	ds_read_b128 v[198:201], v188 offset:52224
	ds_read_b128 v[202:205], v188 offset:53248
	ds_read_b128 v[206:209], v188 offset:54272
	ds_read_b128 v[210:213], v188 offset:55296
	ds_read_b128 v[214:217], v188 offset:56320
	s_add_u32 s4, s78, 0x80
	s_addc_u32 s5, s79, 0
	s_add_i32 m0, s81, 0x18000
	s_nop 0
	global_load_lds_dwordx4 v154, s[4:5]
	s_add_i32 m0, s81, 0x1a000
	s_nop 0
	global_load_lds_dwordx4 v146, s[4:5]
	s_add_u32 s4, vcc_lo, 0x80
	s_addc_u32 s5, vcc_hi, 0
	s_add_i32 m0, s81, 0x8000
	s_nop 0
	global_load_lds_dwordx4 v152, s[4:5]
	s_add_i32 m0, s81, 0xa000
	s_nop 0
	global_load_lds_dwordx4 v144, s[4:5]
	s_add_u32 s4, s78, s26
	s_addc_u32 s5, s79, 0
	s_add_u32 s4, s4, 0x80
	s_addc_u32 s5, s5, 0
	s_add_i32 m0, s81, 0x1c000
	s_nop 0
	global_load_lds_dwordx4 v154, s[4:5]
	s_add_i32 m0, s81, 0x1e000
	s_nop 0
	global_load_lds_dwordx4 v146, s[4:5]
	s_setprio 0
	s_waitcnt vmcnt(8)
	s_waitcnt lgkmcnt(0)
	s_barrier
	v_mfma_f32_16x16x32_bf16 v[60:63], v[128:131], v[162:165], v[60:63]
	v_mfma_f32_16x16x32_bf16 v[56:59], v[136:139], v[162:165], v[56:59]
	v_mfma_f32_16x16x32_bf16 v[52:55], v[128:131], v[194:197], v[52:55]
	v_mfma_f32_16x16x32_bf16 v[48:51], v[136:139], v[194:197], v[48:51]
	v_mfma_f32_16x16x32_bf16 v[28:31], v[128:131], v[202:205], v[28:31]
	v_mfma_f32_16x16x32_bf16 v[20:23], v[136:139], v[202:205], v[20:23]
	v_mfma_f32_16x16x32_bf16 v[24:27], v[128:131], v[210:213], v[24:27]
	v_mfma_f32_16x16x32_bf16 v[16:19], v[136:139], v[210:213], v[16:19]
	v_mfma_f32_16x16x32_bf16 v[60:63], v[132:135], v[190:193], v[60:63]
	v_mfma_f32_16x16x32_bf16 v[56:59], v[140:143], v[190:193], v[56:59]
	v_mfma_f32_16x16x32_bf16 v[52:55], v[132:135], v[198:201], v[52:55]
	v_mfma_f32_16x16x32_bf16 v[48:51], v[140:143], v[198:201], v[48:51]
	v_mfma_f32_16x16x32_bf16 v[28:31], v[132:135], v[206:209], v[28:31]
	v_mfma_f32_16x16x32_bf16 v[20:23], v[140:143], v[206:209], v[20:23]
	v_mfma_f32_16x16x32_bf16 v[24:27], v[132:135], v[214:217], v[24:27]
	v_mfma_f32_16x16x32_bf16 v[16:19], v[140:143], v[214:217], v[16:19]
	v_mfma_f32_16x16x32_bf16 v[44:47], v[218:221], v[162:165], v[44:47]
	v_mfma_f32_16x16x32_bf16 v[36:39], v[226:229], v[162:165], v[36:39]
	v_mfma_f32_16x16x32_bf16 v[40:43], v[218:221], v[194:197], v[40:43]
	v_mfma_f32_16x16x32_bf16 v[32:35], v[226:229], v[194:197], v[32:35]
	v_mfma_f32_16x16x32_bf16 v[12:15], v[218:221], v[202:205], v[12:15]
	v_mfma_f32_16x16x32_bf16 v[4:7], v[226:229], v[202:205], v[4:7]
	v_mfma_f32_16x16x32_bf16 v[8:11], v[218:221], v[210:213], v[8:11]
	v_mfma_f32_16x16x32_bf16 v[0:3], v[226:229], v[210:213], v[0:3]
	v_mfma_f32_16x16x32_bf16 v[44:47], v[222:225], v[190:193], v[44:47]
	v_mfma_f32_16x16x32_bf16 v[36:39], v[230:233], v[190:193], v[36:39]
	v_mfma_f32_16x16x32_bf16 v[40:43], v[222:225], v[198:201], v[40:43]
	v_mfma_f32_16x16x32_bf16 v[32:35], v[230:233], v[198:201], v[32:35]
	v_mfma_f32_16x16x32_bf16 v[12:15], v[222:225], v[206:209], v[12:15]
	v_mfma_f32_16x16x32_bf16 v[4:7], v[230:233], v[206:209], v[4:7]
	v_mfma_f32_16x16x32_bf16 v[8:11], v[222:225], v[214:217], v[8:11]
	v_mfma_f32_16x16x32_bf16 v[0:3], v[230:233], v[214:217], v[0:3]
	s_add_u32 s10, s10, 0x100
	s_addc_u32 s11, s11, 0
	s_add_u32 s84, s84, 0x100
	s_addc_u32 s85, s85, 0
	s_cmp_ge_u32 s72, s76
	s_mov_b32 s78, s72
	s_barrier
	s_cbranch_scc1 .Lkloop_done
	.p2align 6
